# split-phase grid barrier after the layer-0 context-row fix-up; K-slice partial tiles of the context rows moved from the gate/up output buffer to the (dead) output buffer so the gate/up GEMM can start
# speedup vs baseline: 1.0081x; 1.0081x over previous
.LBB0_562:
	s_add_u32 s49, s8, 0x12000
	s_addc_u32 s50, s9, 0
	s_add_u32 s51, s8, 0x60000
	s_addc_u32 s52, s9, 0
	s_add_u32 s53, s8, 0x7400000
	s_addc_u32 s54, s9, 0
	s_add_u32 s55, s8, 0x70000
	s_addc_u32 s56, s9, 0
	s_load_dwordx2 s[94:95], s[82:83], 0xa8
	s_mov_b64 s[16:17], 0x80
	s_waitcnt lgkmcnt(0)
	s_mov_b32 s57, s94
	s_mov_b32 s58, s95
	s_add_i32 m0, s44, 0x18000
	v_lshl_add_u64 v[6:7], v[6:7], 0, s[16:17]
	s_waitcnt vmcnt(2)
	s_barrier
	global_load_lds_dwordx4 v[6:7], off
	v_lshl_add_u64 v[4:5], v[4:5], 0, s[16:17]
	s_add_i32 m0, s44, 0x1a000
	s_add_i32 s59, s44, 0x8000
	s_add_i32 s60, s44, 0xa000
	global_load_lds_dwordx4 v[4:5], off
	v_lshl_add_u64 v[2:3], v[2:3], 0, s[16:17]
	s_mov_b32 m0, s59
	s_add_u32 s6, s34, 0x60080
	global_load_lds_dwordx4 v[2:3], off
	v_lshl_add_u64 v[0:1], v[0:1], 0, s[16:17]
	s_mov_b32 m0, s60
	s_addc_u32 s7, s35, 0
	global_load_lds_dwordx4 v[0:1], off
	s_add_i32 m0, s44, 0x1c000
	v_lshl_add_u64 v[0:1], s[6:7], 0, v[178:179]
	global_load_lds_dwordx4 v[0:1], off
	v_lshl_add_u64 v[0:1], s[6:7], 0, v[182:183]
	s_add_i32 m0, s44, 0x1e000
	v_and_b32_e32 v198, 15, v9
	global_load_lds_dwordx4 v[0:1], off
	v_or_b32_e32 v0, s81, v198
	v_ashrrev_i32_e32 v1, 6, v9
	v_lshlrev_b32_e32 v2, 6, v0
	v_and_b32_e32 v3, 48, v9
	s_movk_i32 s5, 0x3c0
	v_lshlrev_b32_e32 v0, 2, v0
	v_and_or_b32 v2, v2, s5, v3
	v_lshl_add_u32 v4, v1, 10, s79
	v_and_b32_e32 v0, 32, v0
	v_bitop3_b32 v2, v2, v4, v0 bitop3:0xde
	v_lshl_or_b32 v0, v198, 6, v3
	v_lshlrev_b32_e32 v3, 2, v9
	v_add_lshl_u32 v1, v1, s80, 10
	v_and_b32_e32 v3, 32, v3
	v_bitop3_b32 v200, v0, v1, v3 bitop3:0xde
	v_lshrrev_b32_e32 v1, 1, v8
	v_mul_lo_u32 v0, v10, s1
	v_mad_u64_u32 v[0:1], s[20:21], v1, s2, v[0:1]
	v_or_b32_e32 v0, v0, v11
	s_mov_b64 s[6:7], 0x60080
	v_add_lshl_u32 v0, v0, v12, 1
	v_mov_b32_e32 v1, v179
	v_lshl_add_u64 v[184:185], v[0:1], 0, s[6:7]
	v_lshrrev_b32_e32 v1, 1, v13
	v_mul_lo_u32 v0, v14, s1
	v_mad_u64_u32 v[0:1], s[20:21], v1, s2, v[0:1]
	s_waitcnt vmcnt(6)
	s_cmpk_lt_u32 s69, 0x100
	v_or_b32_e32 v0, v0, v15
	s_cselect_b64 s[18:19], -1, 0
	v_add_lshl_u32 v0, v0, v16, 1
	v_mov_b32_e32 v1, v179
	s_add_i32 s61, 0, 0x10000
	s_add_i32 s62, 0, 0x14000
	s_brev_b32 s20, 63
	v_ashrrev_i32_e32 v199, 4, v9
	v_lshl_add_u64 v[186:187], v[0:1], 0, s[6:7]
	v_mov_b64_e32 v[188:189], 0xff
	v_add_u32_e32 v201, s61, v200
	v_add_u32_e32 v202, s62, v200
	v_add_u32_e32 v203, 0, v2
	s_lshl_b32 s63, s78, 2
	s_mov_b32 s21, -1
	s_mov_b32 s64, 0x5000000
	s_barrier
	s_branch .LBB0_565

.Lxb4_rel:
.Lxb4_done:
.LBB0_666:
	s_or_b64 exec, exec, s[4:5]
	s_mov_b32 s1, 0
	s_waitcnt lgkmcnt(0)
	s_barrier
	s_load_dwordx2 s[4:5], s[82:83], 0xb0
	s_load_dwordx2 s[10:11], s[82:83], 0x10
	s_cmpk_lt_i32 s90, 0x400
	s_cselect_b64 s[8:9], -1, 0
	s_mov_b32 s99, 0
	s_load_dwordx2 s[62:63], s[82:83], 0xa8
	s_cmp_eq_u32 s70, 0x100
	s_cselect_b32 s98, 0xd8, 0
	s_lshl_b32 s94, s98, 3
	s_sub_i32 s94, s90, s94
	s_sub_i32 s96, s70, s98
	s_lshl_b32 s96, s96, 3
	s_mov_b32 s0, 0
	s_cmp_lt_i32 s94, 0
	s_cbranch_scc1 .LBB0_671
	s_cmpk_gt_i32 s94, 0x3ff
	s_mov_b32 s0, 0
	s_cbranch_scc1 .LBB0_671
	v_mbcnt_lo_u32_b32 v0, -1, s1
	v_mbcnt_hi_u32_b32 v0, -1, v0
	v_lshlrev_b32_e32 v4, 2, v0
	v_ashrrev_i32_e32 v5, 31, v4
	v_lshlrev_b64 v[8:9], 2, v[4:5]
	s_waitcnt lgkmcnt(0)
	s_sub_u32 s62, s62, 0x9600000
	s_subb_u32 s63, s63, 0
	v_lshl_add_u64 v[2:3], s[4:5], 0, v[8:9]
	s_mov_b64 s[12:13], 0x2a000
	v_cmp_eq_u32_e64 s[6:7], 0, v0
	v_lshl_add_u64 v[0:1], v[2:3], 0, s[12:13]
	s_mov_b64 s[12:13], 0x64000
	s_ashr_i32 s95, s94, 31
	v_lshl_add_u64 v[2:3], v[2:3], 0, s[12:13]
	s_lshl_b64 s[12:13], s[94:95], 2
	s_add_u32 s1, s12, 0x80000
	s_addc_u32 s2, s13, 0
	s_lshl_b64 s[14:15], s[94:95], 11
	v_xor_b32_e32 v24, 0x80, v4
	s_ashr_i32 s97, s96, 31
	v_lshl_add_u64 v[4:5], v[4:5], 1, s[14:15]
	s_mov_b64 s[14:15], 0x9400000
	s_lshl_b64 s[16:17], s[94:95], 12
	s_lshl_b64 s[12:13], s[96:97], 2
	v_lshl_add_u64 v[6:7], v[4:5], 0, s[14:15]
	s_lshl_b64 s[14:15], s[96:97], 11
	v_lshl_add_u64 v[8:9], s[16:17], 0, v[8:9]
	s_lshl_b64 s[16:17], s[96:97], 12
	s_mov_b32 s20, 0x5000000
	v_mov_b32_e32 v25, 0
	s_mov_b32 s21, s94
	s_branch .LBB0_669
.LBB0_668:
	s_or_b64 exec, exec, s[18:19]
	s_add_i32 s21, s21, s96
	s_add_u32 s1, s1, s12
	s_addc_u32 s2, s2, s13
	v_lshl_add_u64 v[6:7], v[6:7], 0, s[14:15]
	v_lshl_add_u64 v[8:9], v[8:9], 0, s[16:17]
	s_cmpk_lt_i32 s21, 0x400
	v_lshl_add_u64 v[4:5], v[4:5], 0, s[14:15]
	s_cbranch_scc0 .LBB0_671
.LBB0_669:
	v_lshl_add_u64 v[20:21], s[62:63], 0, v[8:9]
	v_add_co_u32_e32 v10, vcc, 0x9600000, v20
	v_lshl_add_u64 v[58:59], s[10:11], 0, v[8:9]
	s_waitcnt lgkmcnt(0)
	v_addc_co_u32_e32 v11, vcc, 0, v21, vcc
	v_add_co_u32_e32 v12, vcc, 0x9a00000, v20
	global_load_dwordx4 v[26:29], v[10:11], off
	s_nop 0
	v_addc_co_u32_e32 v13, vcc, 0, v21, vcc
	v_add_co_u32_e32 v14, vcc, 0x9e00000, v20
	v_lshl_add_u64 v[22:23], s[4:5], 0, v[4:5]
	s_nop 0
	v_addc_co_u32_e32 v15, vcc, 0, v21, vcc
	v_add_co_u32_e32 v16, vcc, 0xa200000, v20
	global_load_dwordx4 v[30:33], v[12:13], off
	global_load_dwordx4 v[34:37], v[14:15], off
	v_addc_co_u32_e32 v17, vcc, 0, v21, vcc
	v_add_co_u32_e32 v18, vcc, 0xa600000, v20
	s_waitcnt vmcnt(2)
	v_pk_add_f32 v[26:27], v[26:27], 0 op_sel_hi:[1,0]
	v_addc_co_u32_e32 v19, vcc, 0, v21, vcc
	v_add_co_u32_e32 v20, vcc, 0xaa00000, v20
	global_load_dwordx4 v[38:41], v[16:17], off
	global_load_dwordx4 v[42:45], v[18:19], off
	v_addc_co_u32_e32 v21, vcc, 0, v21, vcc
	global_load_dwordx4 v[46:49], v[20:21], off
	global_load_dwordx4 v[50:53], v[58:59], off
	global_load_dwordx4 v[54:57], v[0:1], off
	v_add_co_u32_e32 v60, vcc, s20, v22
	s_waitcnt vmcnt(6)
	v_pk_add_f32 v[26:27], v[26:27], v[30:31]
	v_addc_co_u32_e32 v61, vcc, 0, v23, vcc
	v_pk_add_f32 v[22:23], v[28:29], 0 op_sel_hi:[1,0]
	s_waitcnt vmcnt(5)
	v_pk_add_f32 v[26:27], v[26:27], v[34:35]
	v_pk_add_f32 v[22:23], v[22:23], v[32:33]
	s_waitcnt vmcnt(4)
	v_pk_add_f32 v[26:27], v[26:27], v[38:39]
	v_pk_add_f32 v[22:23], v[22:23], v[36:37]
	s_waitcnt vmcnt(3)
	v_pk_add_f32 v[26:27], v[26:27], v[42:43]
	v_pk_add_f32 v[22:23], v[22:23], v[40:41]
	s_waitcnt vmcnt(2)
	v_pk_add_f32 v[26:27], v[26:27], v[46:47]
	v_pk_add_f32 v[22:23], v[22:23], v[44:45]
	s_waitcnt vmcnt(0)
	v_pk_fma_f32 v[64:65], v[26:27], v[54:55], v[50:51]
	v_pk_add_f32 v[22:23], v[22:23], v[48:49]
	s_nop 0
	v_pk_fma_f32 v[62:63], v[22:23], v[56:57], v[52:53]
	v_cvt_pk_bf16_f32 v22, v64, v65
	v_cvt_pk_bf16_f32 v23, v62, v63
	global_store_dwordx2 v[60:61], v[22:23], off
	global_load_dwordx4 v[26:29], v[2:3], off
	v_lshl_add_u64 v[22:23], s[4:5], 0, v[6:7]
	s_waitcnt vmcnt(0)
	v_pk_mul_f32 v[28:29], v[62:63], v[28:29]
	v_pk_mul_f32 v[26:27], v[64:65], v[26:27]
	s_nop 0
	v_cvt_pk_bf16_f32 v26, v26, v27
	v_cvt_pk_bf16_f32 v27, v28, v29
	global_store_dwordx2 v[22:23], v[26:27], off
	global_load_dwordx4 v[26:29], v[10:11], off offset:1024
	s_nop 0
	global_load_dwordx4 v[30:33], v[12:13], off offset:1024
	global_load_dwordx4 v[34:37], v[14:15], off offset:1024
	global_load_dwordx4 v[38:41], v[16:17], off offset:1024
	global_load_dwordx4 v[42:45], v[18:19], off offset:1024
	global_load_dwordx4 v[46:49], v[20:21], off offset:1024
	global_load_dwordx4 v[50:53], v[58:59], off offset:1024
	global_load_dwordx4 v[54:57], v[0:1], off offset:1024
	s_waitcnt vmcnt(7)
	v_pk_add_f32 v[28:29], v[28:29], 0 op_sel_hi:[1,0]
	v_pk_add_f32 v[26:27], v[26:27], 0 op_sel_hi:[1,0]
	s_waitcnt vmcnt(6)
	v_pk_add_f32 v[28:29], v[28:29], v[32:33]
	v_pk_add_f32 v[26:27], v[26:27], v[30:31]
	s_waitcnt vmcnt(5)
	v_pk_add_f32 v[28:29], v[28:29], v[36:37]
	v_pk_add_f32 v[26:27], v[26:27], v[34:35]
	s_waitcnt vmcnt(4)
	v_pk_add_f32 v[28:29], v[28:29], v[40:41]
	v_pk_add_f32 v[26:27], v[26:27], v[38:39]
	s_waitcnt vmcnt(3)
	v_pk_add_f32 v[28:29], v[28:29], v[44:45]
	v_pk_add_f32 v[26:27], v[26:27], v[42:43]
	s_waitcnt vmcnt(2)
	v_pk_add_f32 v[28:29], v[28:29], v[48:49]
	v_pk_add_f32 v[26:27], v[26:27], v[46:47]
	s_waitcnt vmcnt(0)
	v_pk_fma_f32 v[66:67], v[28:29], v[56:57], v[52:53]
	v_pk_fma_f32 v[68:69], v[26:27], v[54:55], v[50:51]
	v_cvt_pk_bf16_f32 v27, v66, v67
	v_cvt_pk_bf16_f32 v26, v68, v69
	global_store_dwordx2 v[60:61], v[26:27], off offset:512
	global_load_dwordx4 v[26:29], v[2:3], off offset:1024
	s_waitcnt vmcnt(0)
	v_pk_mul_f32 v[28:29], v[66:67], v[28:29]
	v_pk_mul_f32 v[26:27], v[68:69], v[26:27]
	s_nop 0
	v_cvt_pk_bf16_f32 v26, v26, v27
	v_cvt_pk_bf16_f32 v27, v28, v29
	global_store_dwordx2 v[22:23], v[26:27], off offset:512
	global_load_dwordx4 v[26:29], v[10:11], off offset:2048
	s_nop 0
	global_load_dwordx4 v[30:33], v[12:13], off offset:2048
	global_load_dwordx4 v[34:37], v[14:15], off offset:2048
	global_load_dwordx4 v[38:41], v[16:17], off offset:2048
	global_load_dwordx4 v[42:45], v[18:19], off offset:2048
	global_load_dwordx4 v[46:49], v[20:21], off offset:2048
	global_load_dwordx4 v[50:53], v[58:59], off offset:2048
	global_load_dwordx4 v[54:57], v[0:1], off offset:2048
	s_waitcnt vmcnt(7)
	v_pk_add_f32 v[28:29], v[28:29], 0 op_sel_hi:[1,0]
	v_pk_add_f32 v[26:27], v[26:27], 0 op_sel_hi:[1,0]
	s_waitcnt vmcnt(6)
	v_pk_add_f32 v[28:29], v[28:29], v[32:33]
	v_pk_add_f32 v[26:27], v[26:27], v[30:31]
	s_waitcnt vmcnt(5)
	v_pk_add_f32 v[28:29], v[28:29], v[36:37]
	v_pk_add_f32 v[26:27], v[26:27], v[34:35]
	s_waitcnt vmcnt(4)
	v_pk_add_f32 v[28:29], v[28:29], v[40:41]
	v_pk_add_f32 v[26:27], v[26:27], v[38:39]
	s_waitcnt vmcnt(3)
	v_pk_add_f32 v[28:29], v[28:29], v[44:45]
	v_pk_add_f32 v[26:27], v[26:27], v[42:43]
	s_waitcnt vmcnt(2)
	v_pk_add_f32 v[28:29], v[28:29], v[48:49]
	v_pk_add_f32 v[26:27], v[26:27], v[46:47]
	s_waitcnt vmcnt(0)
	v_pk_fma_f32 v[70:71], v[28:29], v[56:57], v[52:53]
	v_pk_fma_f32 v[72:73], v[26:27], v[54:55], v[50:51]
	v_cvt_pk_bf16_f32 v27, v70, v71
	v_cvt_pk_bf16_f32 v26, v72, v73
	global_store_dwordx2 v[60:61], v[26:27], off offset:1024
	global_load_dwordx4 v[26:29], v[2:3], off offset:2048
	s_waitcnt vmcnt(0)
	v_pk_mul_f32 v[28:29], v[70:71], v[28:29]
	v_pk_mul_f32 v[26:27], v[72:73], v[26:27]
	s_nop 0
	v_cvt_pk_bf16_f32 v26, v26, v27
	v_cvt_pk_bf16_f32 v27, v28, v29
	global_store_dwordx2 v[22:23], v[26:27], off offset:1024
	global_load_dwordx4 v[26:29], v[10:11], off offset:3072
	s_nop 0
	global_load_dwordx4 v[30:33], v[12:13], off offset:3072
	global_load_dwordx4 v[34:37], v[14:15], off offset:3072
	global_load_dwordx4 v[38:41], v[16:17], off offset:3072
	global_load_dwordx4 v[42:45], v[18:19], off offset:3072
	global_load_dwordx4 v[46:49], v[20:21], off offset:3072
	global_load_dwordx4 v[50:53], v[58:59], off offset:3072
	global_load_dwordx4 v[54:57], v[0:1], off offset:3072
	v_mul_f32_e32 v20, v67, v67
	v_fmac_f32_e32 v20, v66, v66
	s_waitcnt vmcnt(7)
	v_pk_add_f32 v[10:11], v[28:29], 0 op_sel_hi:[1,0]
	v_pk_add_f32 v[12:13], v[26:27], 0 op_sel_hi:[1,0]
	s_waitcnt vmcnt(6)
	v_pk_add_f32 v[10:11], v[10:11], v[32:33]
	v_pk_add_f32 v[12:13], v[12:13], v[30:31]
	s_waitcnt vmcnt(5)
	v_pk_add_f32 v[10:11], v[10:11], v[36:37]
	v_pk_add_f32 v[12:13], v[12:13], v[34:35]
	s_waitcnt vmcnt(4)
	v_pk_add_f32 v[10:11], v[10:11], v[40:41]
	v_pk_add_f32 v[12:13], v[12:13], v[38:39]
	s_waitcnt vmcnt(3)
	v_pk_add_f32 v[10:11], v[10:11], v[44:45]
	v_pk_add_f32 v[12:13], v[12:13], v[42:43]
	s_waitcnt vmcnt(2)
	v_pk_add_f32 v[10:11], v[10:11], v[48:49]
	v_pk_add_f32 v[12:13], v[12:13], v[46:47]
	s_waitcnt vmcnt(0)
	v_pk_fma_f32 v[16:17], v[10:11], v[56:57], v[52:53]
	v_pk_fma_f32 v[18:19], v[12:13], v[54:55], v[50:51]
	v_cvt_pk_bf16_f32 v11, v16, v17
	v_cvt_pk_bf16_f32 v10, v18, v19
	global_store_dwordx2 v[60:61], v[10:11], off offset:1536
	global_load_dwordx4 v[12:15], v[2:3], off offset:3072
	v_mul_f32_e32 v10, v65, v65
	v_mul_f32_e32 v11, v63, v63
	v_fmac_f32_e32 v10, v64, v64
	v_fmac_f32_e32 v11, v62, v62
	v_add_f32_e32 v10, v10, v11
	v_mul_f32_e32 v11, v69, v69
	v_fmac_f32_e32 v11, v68, v68
	v_add_f32_e32 v11, v11, v20
	v_add_f32_e32 v10, v10, v11
	v_mul_f32_e32 v11, v73, v73
	v_mul_f32_e32 v20, v71, v71
	v_fmac_f32_e32 v11, v72, v72
	v_fmac_f32_e32 v20, v70, v70
	v_add_f32_e32 v11, v11, v20
	v_add_f32_e32 v10, v10, v11
	v_mul_f32_e32 v11, v19, v19
	v_mul_f32_e32 v20, v17, v17
	v_fmac_f32_e32 v11, v18, v18
	v_fmac_f32_e32 v20, v16, v16
	v_add_f32_e32 v11, v11, v20
	v_add_f32_e32 v10, v10, v11
	ds_swizzle_b32 v11, v10 offset:swizzle(SWAP,1)
	s_waitcnt lgkmcnt(0)
	v_add_f32_e32 v10, v10, v11
	ds_swizzle_b32 v11, v10 offset:swizzle(SWAP,2)
	s_waitcnt lgkmcnt(0)
	v_add_f32_e32 v10, v10, v11
	ds_swizzle_b32 v11, v10 offset:swizzle(SWAP,4)
	s_waitcnt lgkmcnt(0)
	v_add_f32_e32 v10, v10, v11
	ds_swizzle_b32 v11, v10 offset:swizzle(SWAP,8)
	s_waitcnt lgkmcnt(0)
	v_add_f32_e32 v10, v10, v11
	ds_swizzle_b32 v11, v10 offset:swizzle(SWAP,16)
	s_waitcnt lgkmcnt(0)
	v_add_f32_e32 v10, v10, v11
	ds_bpermute_b32 v11, v24, v10
	s_waitcnt vmcnt(0)
	v_pk_mul_f32 v[14:15], v[16:17], v[14:15]
	v_pk_mul_f32 v[12:13], v[18:19], v[12:13]
	s_nop 0
	v_cvt_pk_bf16_f32 v12, v12, v13
	v_cvt_pk_bf16_f32 v13, v14, v15
	global_store_dwordx2 v[22:23], v[12:13], off offset:1536
	s_and_saveexec_b64 s[18:19], s[6:7]
	s_cbranch_execz .LBB0_668
	s_add_u32 s22, s4, s1
	s_waitcnt lgkmcnt(0)
	v_add_f32_e32 v10, v10, v11
	s_addc_u32 s23, s5, s2
	global_store_dword v25, v10, s[22:23]
	s_branch .LBB0_668

.Lxb5_wait:
	buffer_inv sc1
	s_waitcnt vmcnt(0)
	s_branch .Lxb5_done
	buffer_inv sc1
.Lxb5_poll:
	s_branch .Lxb5_done
	global_load_dword v1, v0, s[10:11] offset:1024 sc1
	s_add_u32 s15, s15, 1
	s_waitcnt vmcnt(0)
	v_readfirstlane_b32 s14, v1
	s_cmp_lg_u32 s14, 5
	s_cbranch_scc1 .Lxb5_rel
	s_cmp_lt_u32 s15, 0x40000
	s_cbranch_scc0 .Lxb5_rel
	s_sleep 1
	s_branch .Lxb5_poll

.LBB0_731:
	s_add_i32 s50, s50, 1
	s_mul_i32 s1, s75, s50
	s_mul_hi_u32 s2, s74, s50
	s_add_i32 s2, s2, s1
	s_mul_i32 s1, s74, s50
	s_add_u32 s24, s1, s93
	s_addc_u32 s25, s2, s73
	v_cmp_gt_i64_e32 vcc, s[24:25], v[150:151]
	v_cmp_lt_i64_e64 s[6:7], s[24:25], v[148:149]
	s_cbranch_vccnz .LBB0_733
	s_ashr_i32 s1, s24, 31
	s_lshr_b32 s1, s1, 29
	s_add_i32 s1, s24, s1
	s_ashr_i32 s2, s1, 3
	s_and_b32 s1, s1, -8
	s_sub_i32 s1, s24, s1
	s_cmp_lt_i32 s1, 0
	s_cselect_b32 s5, s41, 0xbb
	s_mul_i32 s1, s1, s5
	s_add_i32 s1, s1, s2
	s_cmp_lt_u32 s1, 0x580
	s_cbranch_scc1 .Ldw_skip
	s_cmp_eq_u32 s99, 1
	s_cbranch_scc1 .Ldw_skip
	s_mov_b32 s99, 1
	s_load_dwordx2 s[60:61], s[82:83], 0xb0
	s_getreg_b32 s94, hwreg(HW_REG_XCC_ID, 0, 4)
	s_and_b32 s94, s94, 15
	s_lshl_b32 s94, s94, 8
	s_add_i32 s94, s94, 0x2400
	v_mov_b32_e32 v231, s94
	s_mov_b32 s95, 0
	s_waitcnt lgkmcnt(0)
.Ldw_poll:
	global_load_dword v232, v231, s[60:61] sc1
	s_waitcnt vmcnt(0)
	v_readfirstlane_b32 s96, v232
	s_cmp_lg_u32 s96, 5
	s_cbranch_scc1 .Ldw_skip
	s_add_u32 s95, s95, 1
	s_cmp_lt_u32 s95, 0x40000
	s_cbranch_scc0 .Ldw_skip
	s_sleep 1
	s_branch .Ldw_poll
.Ldw_skip:
	s_mul_hi_i32 s2, s1, 0x2e8ba2e9
	s_lshr_b32 s5, s2, 31
	s_ashr_i32 s2, s2, 4
	s_add_i32 s2, s2, s5
	s_lshl_b32 s5, s2, 2
	s_sub_i32 s20, 0x44, s5
	s_min_i32 s21, s20, 4
	s_abs_i32 s20, s21
	v_cvt_f32_u32_e32 v0, s20
	s_sub_i32 s23, 0, s20
	s_mulk_i32 s2, 0x58
	s_sub_i32 s1, s1, s2
	v_rcp_iflag_f32_e32 v0, v0
	s_abs_i32 s2, s1
	s_xor_b32 s22, s1, s21
	s_ashr_i32 s22, s22, 31
	v_mul_f32_e32 v0, 0x4f7ffffe, v0
	v_cvt_u32_f32_e32 v0, v0
	s_nop 0
	v_readfirstlane_b32 s24, v0
	s_mul_i32 s23, s23, s24
	s_mul_hi_u32 s23, s24, s23
	s_add_i32 s24, s24, s23
	s_mul_hi_u32 s23, s2, s24
	s_mul_i32 s24, s23, s20
	s_sub_i32 s2, s2, s24
	s_add_i32 s25, s23, 1
	s_sub_i32 s24, s2, s20
	s_cmp_ge_u32 s2, s20
	s_cselect_b32 s23, s25, s23
	s_cselect_b32 s2, s24, s2
	s_add_i32 s24, s23, 1
	s_cmp_ge_u32 s2, s20
	s_cselect_b32 s2, s24, s23
	s_xor_b32 s2, s2, s22
	s_sub_i32 s20, s2, s22
	s_mul_i32 s2, s20, s21
	s_sub_i32 s1, s1, s2
	s_add_i32 s22, s5, s1

.LBB0_759:
	s_waitcnt lgkmcnt(0)
	v_readfirstlane_b32 s1, v2
	v_readfirstlane_b32 s12, v0
	s_lshl_b32 s0, s0, 8
	s_add_u32 s10, s6, s0
	s_addc_u32 s11, s7, 0
	v_mov_b32_e32 v3, 0x1000
	v_mov_b32_e32 v4, 1
	v_mov_b32_e32 v0, 0x2000
	s_mov_b32 s13, 0
.Lxb6_prepoll:
	global_load_dword v1, v0, s[10:11] offset:1024 sc1
	s_add_u32 s13, s13, 1
	s_waitcnt vmcnt(0)
	v_readfirstlane_b32 s14, v1
	s_cmp_lg_u32 s14, 5
	s_cbranch_scc1 .Lxb6_preok
	s_cmp_lt_u32 s13, 0x40000
	s_cbranch_scc0 .Lxb6_preok
	s_sleep 1
	s_branch .Lxb6_prepoll
.Lxb6_preok:
	global_atomic_add v3, v3, v4, s[10:11] offset:1024 sc0
	s_mul_i32 s1, s1, 7
	s_mul_i32 s12, s12, 7
	s_mov_b32 s15, 0
	s_waitcnt vmcnt(0)
	v_readfirstlane_b32 s13, v3
	s_add_u32 s13, s13, 1
	s_cmp_lg_u32 s13, s1
	s_cbranch_scc1 .Lxb6_wait
	buffer_wbl2 sc1
	buffer_inv sc1
	s_waitcnt vmcnt(0)
	v_mov_b32_e32 v3, 0x3000
	global_atomic_add v3, v3, v4, s[6:7] offset:1024 sc0
	s_waitcnt vmcnt(0)
	v_readfirstlane_b32 s13, v3
	s_add_u32 s13, s13, 1
	s_cmp_lg_u32 s13, s12
	s_cbranch_scc1 .Lxb6_poll
	v_mov_b32_e32 v5, 0x3000
	global_atomic_add v0, v4, s[6:7] offset:1024
	global_atomic_add v0, v4, s[6:7] offset:1280
	global_atomic_add v0, v4, s[6:7] offset:1536
	global_atomic_add v0, v4, s[6:7] offset:1792
	global_atomic_add v0, v4, s[6:7] offset:2048
	global_atomic_add v0, v4, s[6:7] offset:2304
	global_atomic_add v0, v4, s[6:7] offset:2560
	global_atomic_add v0, v4, s[6:7] offset:2816
	global_atomic_add v0, v4, s[6:7] offset:3072
	global_atomic_add v0, v4, s[6:7] offset:3328
	global_atomic_add v0, v4, s[6:7] offset:3584
	global_atomic_add v0, v4, s[6:7] offset:3840
	global_atomic_add v5, v4, s[6:7]
	global_atomic_add v5, v4, s[6:7] offset:256
	global_atomic_add v5, v4, s[6:7] offset:512
	global_atomic_add v5, v4, s[6:7] offset:768
	s_waitcnt vmcnt(0)
	s_branch .Lxb6_done
